# S6 SwiGLU epilogue regenerated with packed f32 mul/add (v_pk_mul_f32, v_pk_add_f32), same math and order per element
# baseline (speedup 1.0000x reference)
; __device__ __forceinline__ unsigned cvt_pk_bf16(float lo, float hi) { unsigned r; asm volatile("v_cvt_pk_bf16_f32 %0, %1, %2" : "=v"(r) : "v"(lo), "v"(hi)); return r; }
; __device__ __forceinline__ float swiglu1(float g, float u) { return g * u * __builtin_amdgcn_rcpf(1.0f + __expf(-g)); }
;     __device__ __forceinline__ void operator()(const f32x4 (&acc)[2][2][4][2], const Unit& u, int wr, int wc, int fr, int fq) const {
;         const int row0 = u.pm * BM + wr * 64 + fr, col0 = u.pn * HALF + wc * 32 + 8 * fq;
; #pragma unroll
;         for (int ai = 0; ai < 2; ++ai)
; #pragma unroll
;             for (int m = 0; m < 4; ++m) { bf16_t* rowp = O + (size_t)(row0 + ai * HALF + m * 16) * ldc + col0;
;                 const f32x4 g0 = acc[ai][0][m][0], g1 = acc[ai][0][m][1], u0 = acc[ai][1][m][0], u1 = acc[ai][1][m][1];
;                 u32x4 w; w.x = cvt_pk_bf16(swiglu1(g0[0], u0[0]), swiglu1(g0[1], u0[1])); w.y = cvt_pk_bf16(swiglu1(g0[2], u0[2]), swiglu1(g0[3], u0[3]));
;                 w.z = cvt_pk_bf16(swiglu1(g1[0], u1[0]), swiglu1(g1[1], u1[1])); w.w = cvt_pk_bf16(swiglu1(g1[2], u1[2]), swiglu1(g1[3], u1[3]));
;                 *(u32x4*)rowp = w; }
.LBB0_969:
	s_mov_b32 s48, 0xbfb8aa3b
	s_mov_b32 s50, 1.0
	v_readlane_b32 s14, v254, 6
	v_lshl_or_b32 v142, s30, 7, v146
	v_readlane_b32 s15, v254, 7
	v_lshl_add_u32 v148, s31, 8, v144
	v_ashrrev_i32_e32 v143, 31, v142
	v_mov_b64_e32 v[140:141], s[14:15]
	s_movk_i32 s7, 0x2c00
	v_lshlrev_b64 v[142:143], 1, v[142:143]
	v_pk_mul_f32 v[122:123], v[126:127], v[122:123]
	v_pk_mul_f32 v[124:125], v[128:129], v[124:125]
	v_pk_mul_f32 v[114:115], v[118:119], v[114:115]
	v_pk_mul_f32 v[116:117], v[120:121], v[116:117]
	v_pk_mul_f32 v[126:127], v[126:127], s[48:49] op_sel_hi:[1,0]
	v_pk_mul_f32 v[128:129], v[128:129], s[48:49] op_sel_hi:[1,0]
	v_pk_mul_f32 v[118:119], v[118:119], s[48:49] op_sel_hi:[1,0]
	v_pk_mul_f32 v[120:121], v[120:121], s[48:49] op_sel_hi:[1,0]
	v_exp_f32_e32 v126, v126
	v_exp_f32_e32 v127, v127
	v_exp_f32_e32 v128, v128
	v_exp_f32_e32 v129, v129
	v_exp_f32_e32 v118, v118
	v_exp_f32_e32 v119, v119
	v_exp_f32_e32 v120, v120
	v_exp_f32_e32 v121, v121
	v_pk_add_f32 v[126:127], v[126:127], s[50:51] op_sel_hi:[1,0]
	v_pk_add_f32 v[128:129], v[128:129], s[50:51] op_sel_hi:[1,0]
	v_pk_add_f32 v[118:119], v[118:119], s[50:51] op_sel_hi:[1,0]
	v_pk_add_f32 v[120:121], v[120:121], s[50:51] op_sel_hi:[1,0]
	v_rcp_f32_e32 v126, v126
	v_rcp_f32_e32 v127, v127
	v_rcp_f32_e32 v128, v128
	v_rcp_f32_e32 v129, v129
	v_rcp_f32_e32 v118, v118
	v_rcp_f32_e32 v119, v119
	v_rcp_f32_e32 v120, v120
	v_rcp_f32_e32 v121, v121
	v_pk_mul_f32 v[106:107], v[110:111], v[106:107]
	v_pk_mul_f32 v[108:109], v[112:113], v[108:109]
	v_pk_mul_f32 v[98:99], v[102:103], v[98:99]
	v_pk_mul_f32 v[100:101], v[104:105], v[100:101]
	v_pk_mul_f32 v[110:111], v[110:111], s[48:49] op_sel_hi:[1,0]
	v_pk_mul_f32 v[112:113], v[112:113], s[48:49] op_sel_hi:[1,0]
	v_pk_mul_f32 v[102:103], v[102:103], s[48:49] op_sel_hi:[1,0]
	v_pk_mul_f32 v[104:105], v[104:105], s[48:49] op_sel_hi:[1,0]
	v_pk_mul_f32 v[122:123], v[126:127], v[122:123]
	v_pk_mul_f32 v[124:125], v[128:129], v[124:125]
	v_pk_mul_f32 v[114:115], v[118:119], v[114:115]
	v_pk_mul_f32 v[116:117], v[120:121], v[116:117]
	v_cvt_pk_bf16_f32 v122, v122, v123
	v_cvt_pk_bf16_f32 v123, v124, v125
	v_cvt_pk_bf16_f32 v124, v114, v115
	v_cvt_pk_bf16_f32 v125, v116, v117
	v_mov_b32_e32 v126, v148
	v_mad_i64_i32 v[126:127], s[14:15], v126, s7, v[140:141]
	v_lshl_add_u64 v[126:127], v[126:127], 0, v[142:143]
	global_store_dwordx4 v[126:127], v[122:125], off
	v_exp_f32_e32 v110, v110
	v_exp_f32_e32 v111, v111
	v_exp_f32_e32 v112, v112
	v_exp_f32_e32 v113, v113
	v_exp_f32_e32 v102, v102
	v_exp_f32_e32 v103, v103
	v_exp_f32_e32 v104, v104
	v_exp_f32_e32 v105, v105
	v_pk_add_f32 v[110:111], v[110:111], s[50:51] op_sel_hi:[1,0]
	v_pk_add_f32 v[112:113], v[112:113], s[50:51] op_sel_hi:[1,0]
	v_pk_add_f32 v[102:103], v[102:103], s[50:51] op_sel_hi:[1,0]
	v_pk_add_f32 v[104:105], v[104:105], s[50:51] op_sel_hi:[1,0]
	v_rcp_f32_e32 v110, v110
	v_rcp_f32_e32 v111, v111
	v_rcp_f32_e32 v112, v112
	v_rcp_f32_e32 v113, v113
	v_rcp_f32_e32 v102, v102
	v_rcp_f32_e32 v103, v103
	v_rcp_f32_e32 v104, v104
	v_rcp_f32_e32 v105, v105
	v_pk_mul_f32 v[90:91], v[94:95], v[90:91]
	v_pk_mul_f32 v[92:93], v[96:97], v[92:93]
	v_pk_mul_f32 v[82:83], v[86:87], v[82:83]
	v_pk_mul_f32 v[84:85], v[88:89], v[84:85]
	v_pk_mul_f32 v[94:95], v[94:95], s[48:49] op_sel_hi:[1,0]
	v_pk_mul_f32 v[96:97], v[96:97], s[48:49] op_sel_hi:[1,0]
	v_pk_mul_f32 v[86:87], v[86:87], s[48:49] op_sel_hi:[1,0]
	v_pk_mul_f32 v[88:89], v[88:89], s[48:49] op_sel_hi:[1,0]
	v_pk_mul_f32 v[106:107], v[110:111], v[106:107]
	v_pk_mul_f32 v[108:109], v[112:113], v[108:109]
	v_pk_mul_f32 v[98:99], v[102:103], v[98:99]
	v_pk_mul_f32 v[100:101], v[104:105], v[100:101]
	v_cvt_pk_bf16_f32 v106, v106, v107
	v_cvt_pk_bf16_f32 v107, v108, v109
	v_cvt_pk_bf16_f32 v108, v98, v99
	v_cvt_pk_bf16_f32 v109, v100, v101
	v_or_b32_e32 v110, 16, v148
	v_mad_i64_i32 v[110:111], s[14:15], v110, s7, v[140:141]
	v_lshl_add_u64 v[110:111], v[110:111], 0, v[142:143]
	global_store_dwordx4 v[110:111], v[106:109], off
	v_exp_f32_e32 v94, v94
	v_exp_f32_e32 v95, v95
	v_exp_f32_e32 v96, v96
	v_exp_f32_e32 v97, v97
	v_exp_f32_e32 v86, v86
	v_exp_f32_e32 v87, v87
	v_exp_f32_e32 v88, v88
	v_exp_f32_e32 v89, v89
	v_pk_add_f32 v[94:95], v[94:95], s[50:51] op_sel_hi:[1,0]
	v_pk_add_f32 v[96:97], v[96:97], s[50:51] op_sel_hi:[1,0]
	v_pk_add_f32 v[86:87], v[86:87], s[50:51] op_sel_hi:[1,0]
	v_pk_add_f32 v[88:89], v[88:89], s[50:51] op_sel_hi:[1,0]
	v_rcp_f32_e32 v94, v94
	v_rcp_f32_e32 v95, v95
	v_rcp_f32_e32 v96, v96
	v_rcp_f32_e32 v97, v97
	v_rcp_f32_e32 v86, v86
	v_rcp_f32_e32 v87, v87
	v_rcp_f32_e32 v88, v88
	v_rcp_f32_e32 v89, v89
	v_pk_mul_f32 v[74:75], v[78:79], v[74:75]
	v_pk_mul_f32 v[76:77], v[80:81], v[76:77]
	v_pk_mul_f32 v[66:67], v[70:71], v[66:67]
	v_pk_mul_f32 v[68:69], v[72:73], v[68:69]
	v_pk_mul_f32 v[78:79], v[78:79], s[48:49] op_sel_hi:[1,0]
	v_pk_mul_f32 v[80:81], v[80:81], s[48:49] op_sel_hi:[1,0]
	v_pk_mul_f32 v[70:71], v[70:71], s[48:49] op_sel_hi:[1,0]
	v_pk_mul_f32 v[72:73], v[72:73], s[48:49] op_sel_hi:[1,0]
	v_pk_mul_f32 v[90:91], v[94:95], v[90:91]
	v_pk_mul_f32 v[92:93], v[96:97], v[92:93]
	v_pk_mul_f32 v[82:83], v[86:87], v[82:83]
	v_pk_mul_f32 v[84:85], v[88:89], v[84:85]
	v_cvt_pk_bf16_f32 v90, v90, v91
	v_cvt_pk_bf16_f32 v91, v92, v93
	v_cvt_pk_bf16_f32 v92, v82, v83
	v_cvt_pk_bf16_f32 v93, v84, v85
	v_or_b32_e32 v94, 32, v148
	v_mad_i64_i32 v[94:95], s[14:15], v94, s7, v[140:141]
	v_lshl_add_u64 v[94:95], v[94:95], 0, v[142:143]
	global_store_dwordx4 v[94:95], v[90:93], off
	v_exp_f32_e32 v78, v78
	v_exp_f32_e32 v79, v79
	v_exp_f32_e32 v80, v80
	v_exp_f32_e32 v81, v81
	v_exp_f32_e32 v70, v70
; __device__ __forceinline__ unsigned cvt_pk_bf16(float lo, float hi) { unsigned r; asm volatile("v_cvt_pk_bf16_f32 %0, %1, %2" : "=v"(r) : "v"(lo), "v"(hi)); return r; }
; __device__ __forceinline__ float swiglu1(float g, float u) { return g * u * __builtin_amdgcn_rcpf(1.0f + __expf(-g)); }
;     __device__ __forceinline__ void operator()(const f32x4 (&acc)[2][2][4][2], const Unit& u, int wr, int wc, int fr, int fq) const {
;         const int row0 = u.pm * BM + wr * 64 + fr, col0 = u.pn * HALF + wc * 32 + 8 * fq;
; #pragma unroll
;         for (int ai = 0; ai < 2; ++ai)
; #pragma unroll
;             for (int m = 0; m < 4; ++m) { bf16_t* rowp = O + (size_t)(row0 + ai * HALF + m * 16) * ldc + col0;
;                 const f32x4 g0 = acc[ai][0][m][0], g1 = acc[ai][0][m][1], u0 = acc[ai][1][m][0], u1 = acc[ai][1][m][1];
;                 u32x4 w; w.x = cvt_pk_bf16(swiglu1(g0[0], u0[0]), swiglu1(g0[1], u0[1])); w.y = cvt_pk_bf16(swiglu1(g0[2], u0[2]), swiglu1(g0[3], u0[3]));
;                 w.z = cvt_pk_bf16(swiglu1(g1[0], u1[0]), swiglu1(g1[1], u1[1])); w.w = cvt_pk_bf16(swiglu1(g1[2], u1[2]), swiglu1(g1[3], u1[3]));
;                 *(u32x4*)rowp = w; }
	v_exp_f32_e32 v71, v71
	v_exp_f32_e32 v72, v72
	v_exp_f32_e32 v73, v73
	v_pk_add_f32 v[78:79], v[78:79], s[50:51] op_sel_hi:[1,0]
	v_pk_add_f32 v[80:81], v[80:81], s[50:51] op_sel_hi:[1,0]
	v_pk_add_f32 v[70:71], v[70:71], s[50:51] op_sel_hi:[1,0]
	v_pk_add_f32 v[72:73], v[72:73], s[50:51] op_sel_hi:[1,0]
	v_rcp_f32_e32 v78, v78
	v_rcp_f32_e32 v79, v79
	v_rcp_f32_e32 v80, v80
	v_rcp_f32_e32 v81, v81
	v_rcp_f32_e32 v70, v70
	v_rcp_f32_e32 v71, v71
	v_rcp_f32_e32 v72, v72
	v_rcp_f32_e32 v73, v73
	v_pk_mul_f32 v[58:59], v[62:63], v[58:59]
	v_pk_mul_f32 v[60:61], v[64:65], v[60:61]
	v_pk_mul_f32 v[50:51], v[54:55], v[50:51]
	v_pk_mul_f32 v[52:53], v[56:57], v[52:53]
	v_pk_mul_f32 v[62:63], v[62:63], s[48:49] op_sel_hi:[1,0]
	v_pk_mul_f32 v[64:65], v[64:65], s[48:49] op_sel_hi:[1,0]
	v_pk_mul_f32 v[54:55], v[54:55], s[48:49] op_sel_hi:[1,0]
	v_pk_mul_f32 v[56:57], v[56:57], s[48:49] op_sel_hi:[1,0]
	v_pk_mul_f32 v[74:75], v[78:79], v[74:75]
	v_pk_mul_f32 v[76:77], v[80:81], v[76:77]
	v_pk_mul_f32 v[66:67], v[70:71], v[66:67]
	v_pk_mul_f32 v[68:69], v[72:73], v[68:69]
	v_cvt_pk_bf16_f32 v74, v74, v75
	v_cvt_pk_bf16_f32 v75, v76, v77
	v_cvt_pk_bf16_f32 v76, v66, v67
	v_cvt_pk_bf16_f32 v77, v68, v69
	v_or_b32_e32 v78, 48, v148
	v_mad_i64_i32 v[78:79], s[14:15], v78, s7, v[140:141]
	v_lshl_add_u64 v[78:79], v[78:79], 0, v[142:143]
	global_store_dwordx4 v[78:79], v[74:77], off
	v_exp_f32_e32 v62, v62
	v_exp_f32_e32 v63, v63
	v_exp_f32_e32 v64, v64
	v_exp_f32_e32 v65, v65
	v_exp_f32_e32 v54, v54
	v_exp_f32_e32 v55, v55
	v_exp_f32_e32 v56, v56
	v_exp_f32_e32 v57, v57
	v_pk_add_f32 v[62:63], v[62:63], s[50:51] op_sel_hi:[1,0]
	v_pk_add_f32 v[64:65], v[64:65], s[50:51] op_sel_hi:[1,0]
	v_pk_add_f32 v[54:55], v[54:55], s[50:51] op_sel_hi:[1,0]
	v_pk_add_f32 v[56:57], v[56:57], s[50:51] op_sel_hi:[1,0]
	v_rcp_f32_e32 v62, v62
	v_rcp_f32_e32 v63, v63
	v_rcp_f32_e32 v64, v64
	v_rcp_f32_e32 v65, v65
	v_rcp_f32_e32 v54, v54
	v_rcp_f32_e32 v55, v55
	v_rcp_f32_e32 v56, v56
	v_rcp_f32_e32 v57, v57
	v_pk_mul_f32 v[42:43], v[46:47], v[42:43]
	v_pk_mul_f32 v[44:45], v[48:49], v[44:45]
	v_pk_mul_f32 v[34:35], v[38:39], v[34:35]
	v_pk_mul_f32 v[36:37], v[40:41], v[36:37]
	v_pk_mul_f32 v[46:47], v[46:47], s[48:49] op_sel_hi:[1,0]
	v_pk_mul_f32 v[48:49], v[48:49], s[48:49] op_sel_hi:[1,0]
	v_pk_mul_f32 v[38:39], v[38:39], s[48:49] op_sel_hi:[1,0]
	v_pk_mul_f32 v[40:41], v[40:41], s[48:49] op_sel_hi:[1,0]
	v_pk_mul_f32 v[58:59], v[62:63], v[58:59]
	v_pk_mul_f32 v[60:61], v[64:65], v[60:61]
	v_pk_mul_f32 v[50:51], v[54:55], v[50:51]
	v_pk_mul_f32 v[52:53], v[56:57], v[52:53]
	v_cvt_pk_bf16_f32 v58, v58, v59
	v_cvt_pk_bf16_f32 v59, v60, v61
	v_cvt_pk_bf16_f32 v60, v50, v51
	v_cvt_pk_bf16_f32 v61, v52, v53
	v_add_u32_e32 v62, 0x80, v148
	v_mad_i64_i32 v[62:63], s[14:15], v62, s7, v[140:141]
	v_lshl_add_u64 v[62:63], v[62:63], 0, v[142:143]
	global_store_dwordx4 v[62:63], v[58:61], off
	v_exp_f32_e32 v46, v46
	v_exp_f32_e32 v47, v47
	v_exp_f32_e32 v48, v48
	v_exp_f32_e32 v49, v49
	v_exp_f32_e32 v38, v38
	v_exp_f32_e32 v39, v39
	v_exp_f32_e32 v40, v40
	v_exp_f32_e32 v41, v41
	v_pk_add_f32 v[46:47], v[46:47], s[50:51] op_sel_hi:[1,0]
	v_pk_add_f32 v[48:49], v[48:49], s[50:51] op_sel_hi:[1,0]
	v_pk_add_f32 v[38:39], v[38:39], s[50:51] op_sel_hi:[1,0]
	v_pk_add_f32 v[40:41], v[40:41], s[50:51] op_sel_hi:[1,0]
	v_rcp_f32_e32 v46, v46
	v_rcp_f32_e32 v47, v47
	v_rcp_f32_e32 v48, v48
	v_rcp_f32_e32 v49, v49
	v_rcp_f32_e32 v38, v38
	v_rcp_f32_e32 v39, v39
	v_rcp_f32_e32 v40, v40
	v_rcp_f32_e32 v41, v41
	v_pk_mul_f32 v[26:27], v[30:31], v[26:27]
; __device__ __forceinline__ unsigned cvt_pk_bf16(float lo, float hi) { unsigned r; asm volatile("v_cvt_pk_bf16_f32 %0, %1, %2" : "=v"(r) : "v"(lo), "v"(hi)); return r; }
; __device__ __forceinline__ float swiglu1(float g, float u) { return g * u * __builtin_amdgcn_rcpf(1.0f + __expf(-g)); }
; #define PG8_BAR __builtin_amdgcn_s_barrier()
;     __device__ __forceinline__ void operator()(const f32x4 (&acc)[2][2][4][2], const Unit& u, int wr, int wc, int fr, int fq) const {
;         const int row0 = u.pm * BM + wr * 64 + fr, col0 = u.pn * HALF + wc * 32 + 8 * fq;
; #pragma unroll
;         for (int ai = 0; ai < 2; ++ai)
; #pragma unroll
;             for (int m = 0; m < 4; ++m) { bf16_t* rowp = O + (size_t)(row0 + ai * HALF + m * 16) * ldc + col0;
;                 const f32x4 g0 = acc[ai][0][m][0], g1 = acc[ai][0][m][1], u0 = acc[ai][1][m][0], u1 = acc[ai][1][m][1];
;                 u32x4 w; w.x = cvt_pk_bf16(swiglu1(g0[0], u0[0]), swiglu1(g0[1], u0[1])); w.y = cvt_pk_bf16(swiglu1(g0[2], u0[2]), swiglu1(g0[3], u0[3]));
;                 w.z = cvt_pk_bf16(swiglu1(g1[0], u1[0]), swiglu1(g1[1], u1[1])); w.w = cvt_pk_bf16(swiglu1(g1[2], u1[2]), swiglu1(g1[3], u1[3]));
;                 *(u32x4*)rowp = w; }
; template <class Epi, class Sched, bool ALIGN_EPI = false, bool SP2 = false>
; __device__ __forceinline__ void gemm_phase(PG8_LAS unsigned char* lds, const Gemm g, const Sched& S, const Epi& E) {
;     ...
;         if constexpr (ALIGN_EPI) { if (wr == 0) PG8_BAR; }
;         if constexpr (!Epi::AFTER_DRAIN) { E(acc, cur, wr, wc, fr, fq); S.done(cur); }
;         if (!has_next) break;
; #pragma unroll
;         for (int a = 0; a < 2; ++a)
; #pragma unroll
;             for (int b = 0; b < 2; ++b)
; #pragma unroll
;                 for (int m = 0; m < 4; ++m)
; #pragma unroll
;                     for (int n = 0; n < 2; ++n) acc[a][b][m][n] = (f32x4){0.f, 0.f, 0.f, 0.f};
;         cur = nxt; cA = nA; cB = nB; ++ui;
;         if constexpr (ALIGN_EPI) { if (wr == 1) PG8_BAR; }
	v_pk_mul_f32 v[28:29], v[32:33], v[28:29]
	v_pk_mul_f32 v[18:19], v[22:23], v[18:19]
	v_pk_mul_f32 v[20:21], v[24:25], v[20:21]
	v_pk_mul_f32 v[30:31], v[30:31], s[48:49] op_sel_hi:[1,0]
	v_pk_mul_f32 v[32:33], v[32:33], s[48:49] op_sel_hi:[1,0]
	v_pk_mul_f32 v[22:23], v[22:23], s[48:49] op_sel_hi:[1,0]
	v_pk_mul_f32 v[24:25], v[24:25], s[48:49] op_sel_hi:[1,0]
	v_pk_mul_f32 v[42:43], v[46:47], v[42:43]
	v_pk_mul_f32 v[44:45], v[48:49], v[44:45]
	v_pk_mul_f32 v[34:35], v[38:39], v[34:35]
	v_pk_mul_f32 v[36:37], v[40:41], v[36:37]
	v_cvt_pk_bf16_f32 v42, v42, v43
	v_cvt_pk_bf16_f32 v43, v44, v45
	v_cvt_pk_bf16_f32 v44, v34, v35
	v_cvt_pk_bf16_f32 v45, v36, v37
	v_add_u32_e32 v46, 0x90, v148
	v_mad_i64_i32 v[46:47], s[14:15], v46, s7, v[140:141]
	v_lshl_add_u64 v[46:47], v[46:47], 0, v[142:143]
	global_store_dwordx4 v[46:47], v[42:45], off
	v_exp_f32_e32 v30, v30
	v_exp_f32_e32 v31, v31
	v_exp_f32_e32 v32, v32
	v_exp_f32_e32 v33, v33
	v_exp_f32_e32 v22, v22
	v_exp_f32_e32 v23, v23
	v_exp_f32_e32 v24, v24
	v_exp_f32_e32 v25, v25
	v_pk_add_f32 v[30:31], v[30:31], s[50:51] op_sel_hi:[1,0]
	v_pk_add_f32 v[32:33], v[32:33], s[50:51] op_sel_hi:[1,0]
	v_pk_add_f32 v[22:23], v[22:23], s[50:51] op_sel_hi:[1,0]
	v_pk_add_f32 v[24:25], v[24:25], s[50:51] op_sel_hi:[1,0]
	v_rcp_f32_e32 v30, v30
	v_rcp_f32_e32 v31, v31
	v_rcp_f32_e32 v32, v32
	v_rcp_f32_e32 v33, v33
	v_rcp_f32_e32 v22, v22
	v_rcp_f32_e32 v23, v23
	v_rcp_f32_e32 v24, v24
	v_rcp_f32_e32 v25, v25
	v_pk_mul_f32 v[10:11], v[14:15], v[10:11]
	v_pk_mul_f32 v[12:13], v[16:17], v[12:13]
	v_pk_mul_f32 v[2:3], v[6:7], v[2:3]
	v_pk_mul_f32 v[4:5], v[8:9], v[4:5]
	v_pk_mul_f32 v[14:15], v[14:15], s[48:49] op_sel_hi:[1,0]
	v_pk_mul_f32 v[16:17], v[16:17], s[48:49] op_sel_hi:[1,0]
	v_pk_mul_f32 v[6:7], v[6:7], s[48:49] op_sel_hi:[1,0]
	v_pk_mul_f32 v[8:9], v[8:9], s[48:49] op_sel_hi:[1,0]
	v_pk_mul_f32 v[26:27], v[30:31], v[26:27]
	v_pk_mul_f32 v[28:29], v[32:33], v[28:29]
	v_pk_mul_f32 v[18:19], v[22:23], v[18:19]
	v_pk_mul_f32 v[20:21], v[24:25], v[20:21]
	v_cvt_pk_bf16_f32 v26, v26, v27
	v_cvt_pk_bf16_f32 v27, v28, v29
	v_cvt_pk_bf16_f32 v28, v18, v19
	v_cvt_pk_bf16_f32 v29, v20, v21
	v_add_u32_e32 v30, 0xa0, v148
	v_mad_i64_i32 v[30:31], s[14:15], v30, s7, v[140:141]
	v_lshl_add_u64 v[30:31], v[30:31], 0, v[142:143]
	global_store_dwordx4 v[30:31], v[26:29], off
	v_exp_f32_e32 v14, v14
	v_exp_f32_e32 v15, v15
	v_exp_f32_e32 v16, v16
	v_exp_f32_e32 v17, v17
	v_exp_f32_e32 v6, v6
	v_exp_f32_e32 v7, v7
	v_exp_f32_e32 v8, v8
	v_exp_f32_e32 v9, v9
	v_pk_add_f32 v[14:15], v[14:15], s[50:51] op_sel_hi:[1,0]
	v_pk_add_f32 v[16:17], v[16:17], s[50:51] op_sel_hi:[1,0]
	v_pk_add_f32 v[6:7], v[6:7], s[50:51] op_sel_hi:[1,0]
	v_pk_add_f32 v[8:9], v[8:9], s[50:51] op_sel_hi:[1,0]
	v_rcp_f32_e32 v14, v14
	v_rcp_f32_e32 v15, v15
	v_rcp_f32_e32 v16, v16
	v_rcp_f32_e32 v17, v17
	v_rcp_f32_e32 v6, v6
	v_rcp_f32_e32 v7, v7
	v_rcp_f32_e32 v8, v8
	v_rcp_f32_e32 v9, v9
	v_pk_mul_f32 v[10:11], v[14:15], v[10:11]
	v_pk_mul_f32 v[12:13], v[16:17], v[12:13]
	v_pk_mul_f32 v[2:3], v[6:7], v[2:3]
	v_pk_mul_f32 v[4:5], v[8:9], v[4:5]
	v_cvt_pk_bf16_f32 v10, v10, v11
	v_cvt_pk_bf16_f32 v11, v12, v13
	v_cvt_pk_bf16_f32 v12, v2, v3
	v_cvt_pk_bf16_f32 v13, v4, v5
	v_add_u32_e32 v14, 0xb0, v148
	v_mad_i64_i32 v[14:15], s[14:15], v14, s7, v[140:141]
	v_lshl_add_u64 v[14:15], v[14:15], 0, v[142:143]
	s_mov_b64 s[14:15], -1
	s_andn2_b64 vcc, exec, s[0:1]
	global_store_dwordx4 v[14:15], v[10:13], off
	s_cbranch_vccnz .LBB0_962
	s_andn2_b64 vcc, exec, s[2:3]
	s_cbranch_vccnz .LBB0_961
	s_barrier
	s_branch .LBB0_961
